# E36: residual epilogues load the 4 gate vectors once per tile (rows reuse them), on top of E28
# speedup vs baseline: 1.0016x; 1.0008x over previous
; #define PG8_STAGE(bufoff, gbase, voff) do { _Pragma("unroll") for (int _i = 0; _i < 2; ++_i) \
;     __builtin_amdgcn_global_load_lds((const unsigned*)((const char*)(gbase) + (voff)[_i]), (LAS unsigned*)(lds + (bufoff) + ldsw + _i * 8192), 16, 0, 0); } while (0)
; #define PG8_LDA(dst, b, h) do { _Pragma("unroll") for (int m = 0; m < 4; ++m) _Pragma("unroll") for (int k = 0; k < 2; ++k) dst[m][k] = *(const LAS bf16x8*)(lds + PG8_SA(b, h) + aoff + m * 2048 + k * 1024); } while (0)
; #define PG8_LDB(dst, b, h) do { _Pragma("unroll") for (int n = 0; n < 2; ++n) _Pragma("unroll") for (int k = 0; k < 2; ++k) dst[n][k] = *(const LAS bf16x8*)(lds + PG8_SB(b, h) + boff + n * 2048 + k * 1024); } while (0)
; #define PG8_BAR __builtin_amdgcn_s_barrier()
; template <class Epi, class Sched>
; __device__ __forceinline__ void gemm_phase(LAS unsigned char* lds, const Gemm g, const Sched& S, const Epi& E) {
;     ...
;     for (int t = 0; t < nt; t += 2) {
;       const bool last = (t == nt - 2);
;       const char* a1 = cA + (size_t)(t + 1) * kstep;
;       const char* a2 = last ? nA : cA + (size_t)(t + 2) * kstep; const char* b2 = last ? nB : cB + (size_t)(t + 2) * kstep;
;       const char* a3 = a2 + kstep; const char* b3 = b2 + kstep;
;       PG8_LDB(B0, 0, 0); PG8_SCHED; PG8_LDA(At, 0, 0); PG8_STAGE(PG8_SA(1, 1), a1 + hstepA, voffA);
;       PG8_WAIT_L(8); PG8_BAR; PG8_WAIT_L(0); PG8_MMA(0, 0, At, B0); PG8_BAR; PG8_SCHED;
;       PG8_LDB(B1, 0, 1); PG8_STAGE(PG8_SB(0, 0), b2, voffB);
;       PG8_BAR; PG8_WAIT_L(0); PG8_MMA(0, 1, At, B1); PG8_BAR;
;       PG8_LDA(At, 0, 1); PG8_STAGE(PG8_SA(0, 0), a2, voffA);
;       PG8_BAR; PG8_WAIT_L(0); PG8_MMA(1, 0, At, B0); PG8_BAR; PG8_SCHED;
;       PG8_STAGE(PG8_SB(0, 1), b2 + hstepB, voffB);
;       PG8_WAIT_V(6); PG8_BAR; PG8_MMA(1, 1, At, B1); PG8_BAR;
;       PG8_LDB(B0, 1, 0); PG8_SCHED; PG8_LDA(At, 1, 0); PG8_STAGE(PG8_SA(0, 1), a2 + hstepA, voffA);
;       PG8_WAIT_L(8); PG8_BAR; PG8_WAIT_L(0); PG8_MMA(0, 0, At, B0); PG8_BAR; PG8_SCHED;
;       PG8_LDB(B1, 1, 1); PG8_STAGE(PG8_SB(1, 0), b3, voffB);
;       PG8_BAR; PG8_WAIT_L(0); PG8_MMA(0, 1, At, B1); PG8_BAR;
;       PG8_LDA(At, 1, 1); PG8_STAGE(PG8_SA(1, 0), a3, voffA);
;       PG8_BAR; PG8_WAIT_L(0); PG8_MMA(1, 0, At, B0); PG8_BAR; PG8_SCHED;
;       PG8_STAGE(PG8_SB(1, 1), b3 + hstepB, voffB);
;       PG8_WAIT_V(6); PG8_BAR; PG8_MMA(1, 1, At, B1); PG8_BAR;
.LBB0_2633:
	s_add_u32 s36, s28, 0xfffc0080
	s_addc_u32 s37, s29, -1
	s_add_i32 s76, 16, 0x10000
	v_add_u32_e32 v149, s76, v146
	ds_read_b128 v[136:139], v149
	ds_read_b128 v[140:143], v149 offset:1024
	ds_read_b128 v[150:153], v149 offset:2048
	ds_read_b128 v[154:157], v149 offset:3072
	s_cmp_eq_u32 s86, 12
	s_cselect_b32 s39, s21, s37
	s_cselect_b32 s38, s82, s36
	s_cselect_b32 s37, s19, s85
	s_cselect_b32 s36, s83, s84
	v_lshl_add_u64 v[214:215], s[28:29], 0, v[132:133]
	s_add_i32 m0, s48, 0xc000
	ds_read_b128 v[158:161], v148
	ds_read_b128 v[162:165], v148 offset:1024
	ds_read_b128 v[166:169], v148 offset:2048
	ds_read_b128 v[170:173], v148 offset:3072
	ds_read_b128 v[174:177], v148 offset:4096
	ds_read_b128 v[178:181], v148 offset:5120
	ds_read_b128 v[182:185], v148 offset:6144
	ds_read_b128 v[198:201], v148 offset:7168
	global_load_lds_dwordx4 v[214:215], off
	v_lshl_add_u64 v[214:215], s[28:29], 0, v[134:135]
	s_add_i32 m0, s48, 0xe000
	s_nop 0
	global_load_lds_dwordx4 v[214:215], off
	s_waitcnt lgkmcnt(8)
	s_barrier
	s_waitcnt lgkmcnt(0)
	s_setprio 1
	s_waitcnt lgkmcnt(0)
	v_mfma_f32_16x16x32_bf16 v[124:127], v[136:139], v[158:161], v[124:127]
	v_mfma_f32_16x16x32_bf16 v[120:123], v[150:153], v[158:161], v[120:123]
	v_mfma_f32_16x16x32_bf16 v[112:115], v[136:139], v[166:169], v[112:115]
	v_mfma_f32_16x16x32_bf16 v[104:107], v[150:153], v[166:169], v[104:107]
	v_mfma_f32_16x16x32_bf16 v[96:99], v[136:139], v[174:177], v[96:99]
	v_mfma_f32_16x16x32_bf16 v[88:91], v[150:153], v[174:177], v[88:91]
	v_mfma_f32_16x16x32_bf16 v[80:83], v[136:139], v[182:185], v[80:83]
	v_mfma_f32_16x16x32_bf16 v[72:75], v[150:153], v[182:185], v[72:75]
	v_mfma_f32_16x16x32_bf16 v[124:127], v[140:143], v[162:165], v[124:127]
	v_mfma_f32_16x16x32_bf16 v[120:123], v[154:157], v[162:165], v[120:123]
	v_mfma_f32_16x16x32_bf16 v[112:115], v[140:143], v[170:173], v[112:115]
	v_mfma_f32_16x16x32_bf16 v[104:107], v[154:157], v[170:173], v[104:107]
	v_mfma_f32_16x16x32_bf16 v[96:99], v[140:143], v[178:181], v[96:99]
	v_mfma_f32_16x16x32_bf16 v[88:91], v[154:157], v[178:181], v[88:91]
	v_mfma_f32_16x16x32_bf16 v[80:83], v[140:143], v[198:201], v[80:83]
	v_mfma_f32_16x16x32_bf16 v[72:75], v[154:157], v[198:201], v[72:75]
	s_setprio 0
	s_barrier
	s_add_i32 s87, 16, 0x14000
	s_add_i32 s76, s76, s25
	v_add_u32_e32 v149, s87, v146
	v_lshl_add_u64 v[230:231], s[36:37], 0, v[130:131]
	s_mov_b32 m0, s76
	ds_read_b128 v[214:217], v149
	ds_read_b128 v[218:221], v149 offset:1024
	ds_read_b128 v[222:225], v149 offset:2048
	ds_read_b128 v[226:229], v149 offset:3072
	global_load_lds_dwordx4 v[230:231], off
	v_lshl_add_u64 v[232:233], s[36:37], 0, v[128:129]
	s_add_i32 m0, s76, 0x2000
	s_nop 0
	global_load_lds_dwordx4 v[232:233], off
	s_barrier
	s_waitcnt lgkmcnt(0)
	s_setprio 1
	s_waitcnt lgkmcnt(0)
	v_mfma_f32_16x16x32_bf16 v[116:119], v[214:217], v[158:161], v[116:119]
	v_mfma_f32_16x16x32_bf16 v[108:111], v[222:225], v[158:161], v[108:111]
	v_mfma_f32_16x16x32_bf16 v[100:103], v[214:217], v[166:169], v[100:103]
	v_mfma_f32_16x16x32_bf16 v[92:95], v[222:225], v[166:169], v[92:95]
	v_mfma_f32_16x16x32_bf16 v[84:87], v[214:217], v[174:177], v[84:87]
	v_mfma_f32_16x16x32_bf16 v[76:79], v[222:225], v[174:177], v[76:79]
	v_mfma_f32_16x16x32_bf16 v[68:71], v[214:217], v[182:185], v[68:71]
	v_mfma_f32_16x16x32_bf16 v[64:67], v[222:225], v[182:185], v[64:67]
	v_mfma_f32_16x16x32_bf16 v[116:119], v[218:221], v[162:165], v[116:119]
	v_mfma_f32_16x16x32_bf16 v[108:111], v[226:229], v[162:165], v[108:111]
	v_mfma_f32_16x16x32_bf16 v[100:103], v[218:221], v[170:173], v[100:103]
	v_mfma_f32_16x16x32_bf16 v[92:95], v[226:229], v[170:173], v[92:95]
	v_mfma_f32_16x16x32_bf16 v[84:87], v[218:221], v[178:181], v[84:87]
	v_mfma_f32_16x16x32_bf16 v[76:79], v[226:229], v[178:181], v[76:79]
	v_mfma_f32_16x16x32_bf16 v[68:71], v[218:221], v[198:201], v[68:71]
	v_mfma_f32_16x16x32_bf16 v[64:67], v[226:229], v[198:201], v[64:67]
	s_setprio 0
	s_mov_b32 m0, s48
	v_lshl_add_u64 v[234:235], s[38:39], 0, v[130:131]
	s_barrier
	ds_read_b128 v[158:161], v148 offset:16384
	ds_read_b128 v[162:165], v148 offset:17408
	ds_read_b128 v[166:169], v148 offset:18432
	ds_read_b128 v[170:173], v148 offset:19456
	ds_read_b128 v[174:177], v148 offset:20480
	ds_read_b128 v[178:181], v148 offset:21504
	ds_read_b128 v[182:185], v148 offset:22528
	ds_read_b128 v[198:201], v148 offset:23552
	global_load_lds_dwordx4 v[234:235], off
	v_lshl_add_u64 v[236:237], s[38:39], 0, v[128:129]
	s_mov_b32 m0, s49
	s_nop 0
	global_load_lds_dwordx4 v[236:237], off
	s_barrier
	s_waitcnt lgkmcnt(0)
	s_setprio 1
	s_waitcnt lgkmcnt(0)
	v_mfma_f32_16x16x32_bf16 v[60:63], v[136:139], v[158:161], v[60:63]
	v_mfma_f32_16x16x32_bf16 v[56:59], v[150:153], v[158:161], v[56:59]
	v_mfma_f32_16x16x32_bf16 v[48:51], v[136:139], v[166:169], v[48:51]
	v_mfma_f32_16x16x32_bf16 v[40:43], v[150:153], v[166:169], v[40:43]
	v_mfma_f32_16x16x32_bf16 v[32:35], v[136:139], v[174:177], v[32:35]
	v_mfma_f32_16x16x32_bf16 v[24:27], v[150:153], v[174:177], v[24:27]
	v_mfma_f32_16x16x32_bf16 v[16:19], v[136:139], v[182:185], v[16:19]
	v_mfma_f32_16x16x32_bf16 v[8:11], v[150:153], v[182:185], v[8:11]
	v_mfma_f32_16x16x32_bf16 v[60:63], v[140:143], v[162:165], v[60:63]
	v_mfma_f32_16x16x32_bf16 v[56:59], v[154:157], v[162:165], v[56:59]
	v_mfma_f32_16x16x32_bf16 v[48:51], v[140:143], v[170:173], v[48:51]
	v_mfma_f32_16x16x32_bf16 v[40:43], v[154:157], v[170:173], v[40:43]
	v_mfma_f32_16x16x32_bf16 v[32:35], v[140:143], v[178:181], v[32:35]
	v_mfma_f32_16x16x32_bf16 v[24:27], v[154:157], v[178:181], v[24:27]
	v_mfma_f32_16x16x32_bf16 v[16:19], v[140:143], v[198:201], v[16:19]
	v_mfma_f32_16x16x32_bf16 v[8:11], v[154:157], v[198:201], v[8:11]
	s_setprio 0
	s_barrier
; #define PG8_STAGE(bufoff, gbase, voff) do { _Pragma("unroll") for (int _i = 0; _i < 2; ++_i) \
;     __builtin_amdgcn_global_load_lds((const unsigned*)((const char*)(gbase) + (voff)[_i]), (LAS unsigned*)(lds + (bufoff) + ldsw + _i * 8192), 16, 0, 0); } while (0)
; #define PG8_LDA(dst, b, h) do { _Pragma("unroll") for (int m = 0; m < 4; ++m) _Pragma("unroll") for (int k = 0; k < 2; ++k) dst[m][k] = *(const LAS bf16x8*)(lds + PG8_SA(b, h) + aoff + m * 2048 + k * 1024); } while (0)
; #define PG8_LDB(dst, b, h) do { _Pragma("unroll") for (int n = 0; n < 2; ++n) _Pragma("unroll") for (int k = 0; k < 2; ++k) dst[n][k] = *(const LAS bf16x8*)(lds + PG8_SB(b, h) + boff + n * 2048 + k * 1024); } while (0)
; #define PG8_BAR __builtin_amdgcn_s_barrier()
; template <class Epi, class Sched>
; __device__ __forceinline__ void gemm_phase(LAS unsigned char* lds, const Gemm g, const Sched& S, const Epi& E) {
;     ...
;     for (int t = 0; t < nt; t += 2) {
;       const bool last = (t == nt - 2);
;       const char* a1 = cA + (size_t)(t + 1) * kstep;
;       const char* a2 = last ? nA : cA + (size_t)(t + 2) * kstep; const char* b2 = last ? nB : cB + (size_t)(t + 2) * kstep;
;       const char* a3 = a2 + kstep; const char* b3 = b2 + kstep;
;       PG8_LDB(B0, 0, 0); PG8_SCHED; PG8_LDA(At, 0, 0); PG8_STAGE(PG8_SA(1, 1), a1 + hstepA, voffA);
;       PG8_WAIT_L(8); PG8_BAR; PG8_WAIT_L(0); PG8_MMA(0, 0, At, B0); PG8_BAR; PG8_SCHED;
;       PG8_LDB(B1, 0, 1); PG8_STAGE(PG8_SB(0, 0), b2, voffB);
;       PG8_BAR; PG8_WAIT_L(0); PG8_MMA(0, 1, At, B1); PG8_BAR;
;       PG8_LDA(At, 0, 1); PG8_STAGE(PG8_SA(0, 0), a2, voffA);
;       PG8_BAR; PG8_WAIT_L(0); PG8_MMA(1, 0, At, B0); PG8_BAR; PG8_SCHED;
;       PG8_STAGE(PG8_SB(0, 1), b2 + hstepB, voffB);
;       PG8_WAIT_V(6); PG8_BAR; PG8_MMA(1, 1, At, B1); PG8_BAR;
;       PG8_LDB(B0, 1, 0); PG8_SCHED; PG8_LDA(At, 1, 0); PG8_STAGE(PG8_SA(0, 1), a2 + hstepA, voffA);
;       PG8_WAIT_L(8); PG8_BAR; PG8_WAIT_L(0); PG8_MMA(0, 0, At, B0); PG8_BAR; PG8_SCHED;
;       PG8_LDB(B1, 1, 1); PG8_STAGE(PG8_SB(1, 0), b3, voffB);
;       PG8_BAR; PG8_WAIT_L(0); PG8_MMA(0, 1, At, B1); PG8_BAR;
;       PG8_LDA(At, 1, 1); PG8_STAGE(PG8_SA(1, 0), a3, voffA);
;       PG8_BAR; PG8_WAIT_L(0); PG8_MMA(1, 0, At, B0); PG8_BAR; PG8_SCHED;
;       PG8_STAGE(PG8_SB(1, 1), b3 + hstepB, voffB);
;       PG8_WAIT_V(6); PG8_BAR; PG8_MMA(1, 1, At, B1); PG8_BAR;
	s_add_u32 s76, s36, 0x40000
	s_addc_u32 s77, s37, 0
	s_add_i32 s87, s87, s25
	v_lshl_add_u64 v[136:137], s[76:77], 0, v[130:131]
	s_mov_b32 m0, s87
	s_nop 0
	global_load_lds_dwordx4 v[136:137], off
	v_lshl_add_u64 v[136:137], s[76:77], 0, v[128:129]
	s_add_i32 m0, s87, 0x2000
	s_nop 0
	global_load_lds_dwordx4 v[136:137], off
	s_waitcnt vmcnt(6)
	s_barrier
	s_setprio 1
	v_mfma_f32_16x16x32_bf16 v[52:55], v[214:217], v[158:161], v[52:55]
	v_mfma_f32_16x16x32_bf16 v[44:47], v[222:225], v[158:161], v[44:47]
	v_mfma_f32_16x16x32_bf16 v[36:39], v[214:217], v[166:169], v[36:39]
	v_mfma_f32_16x16x32_bf16 v[28:31], v[222:225], v[166:169], v[28:31]
	v_mfma_f32_16x16x32_bf16 v[20:23], v[214:217], v[174:177], v[20:23]
	v_mfma_f32_16x16x32_bf16 v[12:15], v[222:225], v[174:177], v[12:15]
	v_mfma_f32_16x16x32_bf16 v[4:7], v[214:217], v[182:185], v[4:7]
	v_mfma_f32_16x16x32_bf16 v[0:3], v[222:225], v[182:185], v[0:3]
	v_mfma_f32_16x16x32_bf16 v[52:55], v[218:221], v[162:165], v[52:55]
	v_mfma_f32_16x16x32_bf16 v[44:47], v[226:229], v[162:165], v[44:47]
	v_mfma_f32_16x16x32_bf16 v[36:39], v[218:221], v[170:173], v[36:39]
	v_mfma_f32_16x16x32_bf16 v[28:31], v[226:229], v[170:173], v[28:31]
	v_mfma_f32_16x16x32_bf16 v[20:23], v[218:221], v[178:181], v[20:23]
	v_mfma_f32_16x16x32_bf16 v[12:15], v[226:229], v[178:181], v[12:15]
	v_mfma_f32_16x16x32_bf16 v[4:7], v[218:221], v[198:201], v[4:7]
	v_mfma_f32_16x16x32_bf16 v[0:3], v[226:229], v[198:201], v[0:3]
	s_setprio 0
	s_add_i32 s76, 16, 0x18000
	v_add_u32_e32 v149, s76, v146
	s_barrier
	ds_read_b128 v[136:139], v149
	ds_read_b128 v[140:143], v149 offset:1024
	ds_read_b128 v[150:153], v149 offset:2048
	ds_read_b128 v[154:157], v149 offset:3072
	s_add_u32 s38, s38, 0x40000
	s_addc_u32 s39, s39, 0
	s_mov_b32 m0, s51
	v_lshl_add_u64 v[214:215], s[38:39], 0, v[130:131]
	ds_read_b128 v[158:161], v148 offset:32768
	ds_read_b128 v[162:165], v148 offset:33792
	ds_read_b128 v[166:169], v148 offset:34816
	ds_read_b128 v[170:173], v148 offset:35840
	ds_read_b128 v[174:177], v148 offset:36864
	ds_read_b128 v[178:181], v148 offset:37888
	ds_read_b128 v[182:185], v148 offset:38912
	ds_read_b128 v[198:201], v148 offset:39936
	global_load_lds_dwordx4 v[214:215], off
	v_lshl_add_u64 v[214:215], s[38:39], 0, v[128:129]
	s_mov_b32 m0, s58
	s_nop 0
	global_load_lds_dwordx4 v[214:215], off
	s_waitcnt lgkmcnt(8)
	s_barrier
	s_waitcnt lgkmcnt(0)
	s_setprio 1
	s_waitcnt lgkmcnt(0)
	v_mfma_f32_16x16x32_bf16 v[124:127], v[136:139], v[158:161], v[124:127]
	v_mfma_f32_16x16x32_bf16 v[120:123], v[150:153], v[158:161], v[120:123]
	v_mfma_f32_16x16x32_bf16 v[112:115], v[136:139], v[166:169], v[112:115]
	v_mfma_f32_16x16x32_bf16 v[104:107], v[150:153], v[166:169], v[104:107]
	v_mfma_f32_16x16x32_bf16 v[96:99], v[136:139], v[174:177], v[96:99]
	v_mfma_f32_16x16x32_bf16 v[88:91], v[150:153], v[174:177], v[88:91]
	v_mfma_f32_16x16x32_bf16 v[80:83], v[136:139], v[182:185], v[80:83]
	v_mfma_f32_16x16x32_bf16 v[72:75], v[150:153], v[182:185], v[72:75]
	v_mfma_f32_16x16x32_bf16 v[124:127], v[140:143], v[162:165], v[124:127]
	v_mfma_f32_16x16x32_bf16 v[120:123], v[154:157], v[162:165], v[120:123]
	v_mfma_f32_16x16x32_bf16 v[112:115], v[140:143], v[170:173], v[112:115]
	v_mfma_f32_16x16x32_bf16 v[104:107], v[154:157], v[170:173], v[104:107]
	v_mfma_f32_16x16x32_bf16 v[96:99], v[140:143], v[178:181], v[96:99]
	v_mfma_f32_16x16x32_bf16 v[88:91], v[154:157], v[178:181], v[88:91]
	v_mfma_f32_16x16x32_bf16 v[80:83], v[140:143], v[198:201], v[80:83]
	v_mfma_f32_16x16x32_bf16 v[72:75], v[154:157], v[198:201], v[72:75]
	s_setprio 0
	s_barrier
	s_add_i32 s38, 16, 0x1c000
	s_add_i32 s39, s76, s25
	v_add_u32_e32 v149, s38, v146
	v_lshl_add_u64 v[230:231], v[230:231], 0, s[62:63]
	s_mov_b32 m0, s39
	ds_read_b128 v[214:217], v149
	ds_read_b128 v[218:221], v149 offset:1024
	ds_read_b128 v[222:225], v149 offset:2048
	ds_read_b128 v[226:229], v149 offset:3072
	global_load_lds_dwordx4 v[230:231], off
	v_lshl_add_u64 v[230:231], v[232:233], 0, s[62:63]
	s_add_i32 m0, s39, 0x2000
	s_nop 0
	global_load_lds_dwordx4 v[230:231], off
	s_barrier
	s_waitcnt lgkmcnt(0)
	s_setprio 1
	s_waitcnt lgkmcnt(0)
	v_mfma_f32_16x16x32_bf16 v[116:119], v[214:217], v[158:161], v[116:119]
	v_mfma_f32_16x16x32_bf16 v[108:111], v[222:225], v[158:161], v[108:111]
	v_mfma_f32_16x16x32_bf16 v[100:103], v[214:217], v[166:169], v[100:103]
	v_mfma_f32_16x16x32_bf16 v[92:95], v[222:225], v[166:169], v[92:95]
	v_mfma_f32_16x16x32_bf16 v[84:87], v[214:217], v[174:177], v[84:87]
	v_mfma_f32_16x16x32_bf16 v[76:79], v[222:225], v[174:177], v[76:79]
	v_mfma_f32_16x16x32_bf16 v[68:71], v[214:217], v[182:185], v[68:71]
	v_mfma_f32_16x16x32_bf16 v[64:67], v[222:225], v[182:185], v[64:67]
	v_mfma_f32_16x16x32_bf16 v[116:119], v[218:221], v[162:165], v[116:119]
	v_mfma_f32_16x16x32_bf16 v[108:111], v[226:229], v[162:165], v[108:111]
	v_mfma_f32_16x16x32_bf16 v[100:103], v[218:221], v[170:173], v[100:103]
	v_mfma_f32_16x16x32_bf16 v[92:95], v[226:229], v[170:173], v[92:95]
	v_mfma_f32_16x16x32_bf16 v[84:87], v[218:221], v[178:181], v[84:87]
	v_mfma_f32_16x16x32_bf16 v[76:79], v[226:229], v[178:181], v[76:79]
	v_mfma_f32_16x16x32_bf16 v[68:71], v[218:221], v[198:201], v[68:71]
	v_mfma_f32_16x16x32_bf16 v[64:67], v[226:229], v[198:201], v[64:67]
	s_setprio 0
	s_mov_b32 m0, s69
	v_lshl_add_u64 v[230:231], v[234:235], 0, s[62:63]
	s_barrier
	ds_read_b128 v[158:161], v148 offset:49152
	ds_read_b128 v[162:165], v148 offset:50176
	ds_read_b128 v[166:169], v148 offset:51200
	ds_read_b128 v[170:173], v148 offset:52224
	ds_read_b128 v[174:177], v148 offset:53248
	ds_read_b128 v[178:181], v148 offset:54272
	ds_read_b128 v[182:185], v148 offset:55296
	ds_read_b128 v[198:201], v148 offset:56320
	global_load_lds_dwordx4 v[230:231], off
	v_lshl_add_u64 v[230:231], v[236:237], 0, s[62:63]
	s_mov_b32 m0, s74
	s_nop 0
	global_load_lds_dwordx4 v[230:231], off
	s_barrier
; #define PG8_STAGE(bufoff, gbase, voff) do { _Pragma("unroll") for (int _i = 0; _i < 2; ++_i) \
;     __builtin_amdgcn_global_load_lds((const unsigned*)((const char*)(gbase) + (voff)[_i]), (LAS unsigned*)(lds + (bufoff) + ldsw + _i * 8192), 16, 0, 0); } while (0)
; #define PG8_MMA(ai, bj, At, Bt) do { __builtin_amdgcn_s_setprio(1); _Pragma("unroll") for (int m = 0; m < 4; ++m) _Pragma("unroll") for (int n = 0; n < 2; ++n) _Pragma("unroll") for (int k = 0; k < 2; ++k) \
;     acc[ai][bj][m][n] = __builtin_amdgcn_mfma_f32_16x16x32_bf16(Bt[n][k], At[m][k], acc[ai][bj][m][n], 0, 0, 0); __builtin_amdgcn_s_setprio(0); } while (0)
; #define PG8_WAIT_V(n) asm volatile("s_waitcnt vmcnt(" #n ")" ::: "memory")
; #define PG8_WAIT_L(n) asm volatile("s_waitcnt lgkmcnt(" #n ")" ::: "memory")
; #define PG8_BAR __builtin_amdgcn_s_barrier()
; #define PG8_SCHED __builtin_amdgcn_sched_barrier(0)
; template <class Epi, class Sched>
; __device__ __forceinline__ void gemm_phase(LAS unsigned char* lds, const Gemm g, const Sched& S, const Epi& E) {
;     ...
;       PG8_BAR; PG8_WAIT_L(0); PG8_MMA(1, 0, At, B0); PG8_BAR; PG8_SCHED;
;       PG8_STAGE(PG8_SB(1, 1), b3 + hstepB, voffB);
;       PG8_WAIT_V(6); PG8_BAR; PG8_MMA(1, 1, At, B1); PG8_BAR;
;     }
;     E(acc, cur, wr, wc, fr, fq);
	s_waitcnt lgkmcnt(0)
	s_setprio 1
	s_waitcnt lgkmcnt(0)
	v_mfma_f32_16x16x32_bf16 v[60:63], v[136:139], v[158:161], v[60:63]
	v_mfma_f32_16x16x32_bf16 v[56:59], v[150:153], v[158:161], v[56:59]
	v_mfma_f32_16x16x32_bf16 v[48:51], v[136:139], v[166:169], v[48:51]
	v_mfma_f32_16x16x32_bf16 v[40:43], v[150:153], v[166:169], v[40:43]
	v_mfma_f32_16x16x32_bf16 v[32:35], v[136:139], v[174:177], v[32:35]
	v_mfma_f32_16x16x32_bf16 v[24:27], v[150:153], v[174:177], v[24:27]
	v_mfma_f32_16x16x32_bf16 v[16:19], v[136:139], v[182:185], v[16:19]
	v_mfma_f32_16x16x32_bf16 v[8:11], v[150:153], v[182:185], v[8:11]
	v_mfma_f32_16x16x32_bf16 v[60:63], v[140:143], v[162:165], v[60:63]
	v_mfma_f32_16x16x32_bf16 v[56:59], v[154:157], v[162:165], v[56:59]
	v_mfma_f32_16x16x32_bf16 v[48:51], v[140:143], v[170:173], v[48:51]
	v_mfma_f32_16x16x32_bf16 v[40:43], v[154:157], v[170:173], v[40:43]
	v_mfma_f32_16x16x32_bf16 v[32:35], v[140:143], v[178:181], v[32:35]
	v_mfma_f32_16x16x32_bf16 v[24:27], v[154:157], v[178:181], v[24:27]
	v_mfma_f32_16x16x32_bf16 v[16:19], v[140:143], v[198:201], v[16:19]
	v_mfma_f32_16x16x32_bf16 v[8:11], v[154:157], v[198:201], v[8:11]
	s_setprio 0
	s_barrier
	s_add_u32 s36, s36, 0x40080
	s_addc_u32 s37, s37, 0
	s_add_i32 s38, s38, s25
	v_lshl_add_u64 v[136:137], s[36:37], 0, v[130:131]
	s_mov_b32 m0, s38
	s_nop 0
	global_load_lds_dwordx4 v[136:137], off
	v_lshl_add_u64 v[136:137], s[36:37], 0, v[128:129]
	s_add_i32 m0, s38, 0x2000
	s_nop 0
	global_load_lds_dwordx4 v[136:137], off
	s_waitcnt vmcnt(6)
	s_barrier
	s_setprio 1
	v_mfma_f32_16x16x32_bf16 v[52:55], v[214:217], v[158:161], v[52:55]
	v_mfma_f32_16x16x32_bf16 v[44:47], v[222:225], v[158:161], v[44:47]
	v_mfma_f32_16x16x32_bf16 v[36:39], v[214:217], v[166:169], v[36:39]
	v_mfma_f32_16x16x32_bf16 v[28:31], v[222:225], v[166:169], v[28:31]
	v_mfma_f32_16x16x32_bf16 v[20:23], v[214:217], v[174:177], v[20:23]
	v_mfma_f32_16x16x32_bf16 v[12:15], v[222:225], v[174:177], v[12:15]
	v_mfma_f32_16x16x32_bf16 v[4:7], v[214:217], v[182:185], v[4:7]
	v_mfma_f32_16x16x32_bf16 v[0:3], v[222:225], v[182:185], v[0:3]
	v_mfma_f32_16x16x32_bf16 v[52:55], v[218:221], v[162:165], v[52:55]
	v_mfma_f32_16x16x32_bf16 v[44:47], v[226:229], v[162:165], v[44:47]
	v_mfma_f32_16x16x32_bf16 v[36:39], v[218:221], v[170:173], v[36:39]
	v_mfma_f32_16x16x32_bf16 v[28:31], v[226:229], v[170:173], v[28:31]
	v_mfma_f32_16x16x32_bf16 v[20:23], v[218:221], v[178:181], v[20:23]
	v_mfma_f32_16x16x32_bf16 v[12:15], v[226:229], v[178:181], v[12:15]
	v_mfma_f32_16x16x32_bf16 v[4:7], v[218:221], v[198:201], v[4:7]
	v_mfma_f32_16x16x32_bf16 v[0:3], v[226:229], v[198:201], v[0:3]
	s_setprio 0
	s_add_i32 s86, s86, 2
	s_add_u32 s28, s28, 0x100
	s_addc_u32 s29, s29, 0
	s_add_u32 s84, s84, 0x100
	s_addc_u32 s85, s85, 0
	s_cmp_gt_u32 s86, 13
	s_barrier
	s_cbranch_scc0 .LBB0_2633
	v_lshl_add_u32 v140, s79, 8, v145
	v_lshl_or_b32 v136, s78, 8, v147
	v_ashrrev_i32_e32 v141, 31, v140
	v_lshlrev_b64 v[138:139], 12, v[140:141]
	v_ashrrev_i32_e32 v137, 31, v136
	v_lshlrev_b64 v[142:143], 2, v[136:137]
	v_lshl_add_u64 v[136:137], s[14:15], 0, v[138:139]
	v_lshl_add_u64 v[138:139], s[16:17], 0, v[138:139]
	s_mov_b32 s28, 0xfff00000
	v_mov_b32_e32 v141, s66
	v_mov_b32_e32 v149, s68
	v_cmp_gt_i32_e32 vcc, s73, v140
	v_mov_b32_e32 v150, s59
	v_mov_b32_e32 v151, s67
	v_lshl_add_u64 v[138:139], v[138:139], 0, v[142:143]
	s_mov_b32 s29, -1
	v_cndmask_b32_e32 v153, v141, v149, vcc
	v_cndmask_b32_e32 v152, v150, v151, vcc
	v_lshl_add_u64 v[136:137], v[136:137], 0, v[142:143]
	v_lshl_add_u64 v[156:157], v[138:139], 0, s[28:29]
	v_lshl_add_u64 v[160:161], v[152:153], 0, v[142:143]
	v_cndmask_b32_e64 v163, v157, v137, s[8:9]
	v_cndmask_b32_e64 v162, v156, v136, s[8:9]
	global_load_dwordx4 v[214:217], v[160:161], off
	global_load_dwordx4 v[218:221], v[160:161], off offset:64
	global_load_dwordx4 v[222:225], v[160:161], off offset:512
	global_load_dwordx4 v[226:229], v[160:161], off offset:576
	global_load_dwordx4 v[230:233], v[162:163], off
	global_load_dwordx4 v[234:237], v[162:163], off offset:64
	global_load_dwordx4 v[238:241], v[162:163], off offset:512
	global_load_dwordx4 v[242:245], v[162:163], off offset:576
	s_mov_b32 s28, 0xfff10000
	s_mov_b32 s29, -1
	s_movk_i32 s19, 0x80
	s_mov_b32 s87, 0x80000
	s_mov_b32 s78, s18
	s_mov_b32 s79, s20
	s_mov_b64 s[36:37], s[26:27]
	s_movk_i32 s86, 0x4100
	s_waitcnt vmcnt(3)
	v_pk_fma_f32 v[126:127], v[126:127], v[216:217], v[232:233]
	v_pk_fma_f32 v[124:125], v[124:125], v[214:215], v[230:231]
	global_store_dwordx4 v[136:137], v[124:127], off
	s_nop 0
	s_waitcnt vmcnt(3)
	v_pk_fma_f32 v[122:123], v[122:123], v[220:221], v[236:237]
	v_pk_fma_f32 v[120:121], v[120:121], v[218:219], v[234:235]
	global_store_dwordx4 v[136:137], v[120:123], off offset:64
	s_nop 0
	v_lshl_add_u64 v[152:153], v[138:139], 0, s[28:29]
	s_mov_b32 s28, 0xfff20000
	s_mov_b32 s29, -1
	s_waitcnt vmcnt(3)
	v_pk_fma_f32 v[118:119], v[118:119], v[224:225], v[240:241]
	v_pk_fma_f32 v[116:117], v[116:117], v[222:223], v[238:239]
	global_store_dwordx4 v[136:137], v[116:119], off offset:512
	s_nop 0
	v_or_b32_e32 v124, 16, v140
	v_ashrrev_i32_e32 v125, 31, v124
	v_cmp_gt_i32_e32 vcc, s73, v124
	v_lshlrev_b64 v[124:125], 12, v[124:125]
	v_lshl_add_u64 v[124:125], s[14:15], 0, v[124:125]
	v_cndmask_b32_e32 v127, v141, v149, vcc
	v_cndmask_b32_e32 v126, v150, v151, vcc
	v_lshl_add_u64 v[126:127], v[126:127], 0, v[142:143]
	v_lshl_add_u64 v[124:125], v[124:125], 0, v[142:143]
	v_cndmask_b32_e64 v153, v153, v125, s[8:9]
	v_cndmask_b32_e64 v152, v152, v124, s[8:9]
	s_waitcnt vmcnt(3)
	v_pk_fma_f32 v[110:111], v[110:111], v[228:229], v[244:245]
	v_pk_fma_f32 v[108:109], v[108:109], v[226:227], v[242:243]
	global_store_dwordx4 v[136:137], v[108:111], off offset:576
	global_load_dwordx4 v[230:233], v[152:153], off
	global_load_dwordx4 v[234:237], v[152:153], off offset:64
	global_load_dwordx4 v[238:241], v[152:153], off offset:512
	global_load_dwordx4 v[242:245], v[152:153], off offset:576
	s_nop 0
	s_waitcnt vmcnt(3)
	v_pk_fma_f32 v[110:111], v[114:115], v[216:217], v[232:233]
	v_pk_fma_f32 v[108:109], v[112:113], v[214:215], v[230:231]
	global_store_dwordx4 v[124:125], v[108:111], off
	s_nop 0
	s_waitcnt vmcnt(3)
	v_pk_fma_f32 v[106:107], v[106:107], v[220:221], v[236:237]
	v_pk_fma_f32 v[104:105], v[104:105], v[218:219], v[234:235]
	global_store_dwordx4 v[124:125], v[104:107], off offset:64
	s_nop 0
	v_lshl_add_u64 v[112:113], v[138:139], 0, s[28:29]
	s_mov_b32 s28, 0xfff30000
	s_mov_b32 s29, -1
	s_waitcnt vmcnt(3)
	v_pk_fma_f32 v[102:103], v[102:103], v[224:225], v[240:241]
	v_pk_fma_f32 v[100:101], v[100:101], v[222:223], v[238:239]
	global_store_dwordx4 v[124:125], v[100:103], off offset:512
	s_nop 0
	v_or_b32_e32 v108, 32, v140
	v_ashrrev_i32_e32 v109, 31, v108
	v_cmp_gt_i32_e32 vcc, s73, v108
	v_lshlrev_b64 v[108:109], 12, v[108:109]
	v_lshl_add_u64 v[108:109], s[14:15], 0, v[108:109]
	v_cndmask_b32_e32 v111, v141, v149, vcc
	v_cndmask_b32_e32 v110, v150, v151, vcc
	v_lshl_add_u64 v[110:111], v[110:111], 0, v[142:143]
	v_lshl_add_u64 v[108:109], v[108:109], 0, v[142:143]
	v_cndmask_b32_e64 v113, v113, v109, s[8:9]
	v_cndmask_b32_e64 v112, v112, v108, s[8:9]
	s_waitcnt vmcnt(3)
	v_pk_fma_f32 v[94:95], v[94:95], v[228:229], v[244:245]
	v_pk_fma_f32 v[92:93], v[92:93], v[226:227], v[242:243]
	global_store_dwordx4 v[124:125], v[92:95], off offset:576
	global_load_dwordx4 v[230:233], v[112:113], off
	global_load_dwordx4 v[234:237], v[112:113], off offset:64
	global_load_dwordx4 v[238:241], v[112:113], off offset:512
	global_load_dwordx4 v[242:245], v[112:113], off offset:576
	s_nop 0
	s_waitcnt vmcnt(3)
	v_pk_fma_f32 v[94:95], v[98:99], v[216:217], v[232:233]
	v_pk_fma_f32 v[92:93], v[96:97], v[214:215], v[230:231]
	global_store_dwordx4 v[108:109], v[92:95], off
	s_nop 0
	s_waitcnt vmcnt(3)
	v_pk_fma_f32 v[90:91], v[90:91], v[220:221], v[236:237]
	v_pk_fma_f32 v[88:89], v[88:89], v[218:219], v[234:235]
	global_store_dwordx4 v[108:109], v[88:91], off offset:64
	s_nop 0
	v_lshl_add_u64 v[96:97], v[138:139], 0, s[28:29]
	s_mov_b64 s[28:29], 0x80000
	s_waitcnt vmcnt(3)
	v_pk_fma_f32 v[86:87], v[86:87], v[224:225], v[240:241]
	v_pk_fma_f32 v[84:85], v[84:85], v[222:223], v[238:239]
	global_store_dwordx4 v[108:109], v[84:87], off offset:512
	s_nop 0
	v_or_b32_e32 v92, 48, v140
	v_ashrrev_i32_e32 v93, 31, v92
	v_cmp_gt_i32_e32 vcc, s73, v92
	v_lshlrev_b64 v[92:93], 12, v[92:93]
	v_lshl_add_u64 v[92:93], s[14:15], 0, v[92:93]
	v_cndmask_b32_e32 v95, v141, v149, vcc
	v_cndmask_b32_e32 v94, v150, v151, vcc
	v_lshl_add_u64 v[94:95], v[94:95], 0, v[142:143]
	v_lshl_add_u64 v[92:93], v[92:93], 0, v[142:143]
	v_cndmask_b32_e64 v97, v97, v93, s[8:9]
	v_cndmask_b32_e64 v96, v96, v92, s[8:9]
	v_cmp_gt_i32_e32 vcc, s19, v140
	s_mov_b32 s19, 0x90000
	s_waitcnt vmcnt(3)
	v_pk_fma_f32 v[78:79], v[78:79], v[228:229], v[244:245]
	v_pk_fma_f32 v[76:77], v[76:77], v[226:227], v[242:243]
	global_store_dwordx4 v[108:109], v[76:79], off offset:576
	global_load_dwordx4 v[230:233], v[96:97], off
	global_load_dwordx4 v[234:237], v[96:97], off offset:64
	global_load_dwordx4 v[238:241], v[96:97], off offset:512
	global_load_dwordx4 v[242:245], v[96:97], off offset:576
	s_nop 0
	s_waitcnt vmcnt(3)
	v_pk_fma_f32 v[78:79], v[82:83], v[216:217], v[232:233]
	v_pk_fma_f32 v[76:77], v[80:81], v[214:215], v[230:231]
	global_store_dwordx4 v[92:93], v[76:79], off
	s_nop 0
	s_waitcnt vmcnt(3)
	v_pk_fma_f32 v[74:75], v[74:75], v[220:221], v[236:237]
	v_pk_fma_f32 v[72:73], v[72:73], v[218:219], v[234:235]
	global_store_dwordx4 v[92:93], v[72:75], off offset:64
	s_nop 0
	s_waitcnt vmcnt(3)
	v_pk_fma_f32 v[70:71], v[70:71], v[224:225], v[240:241]
	v_pk_fma_f32 v[68:69], v[68:69], v[222:223], v[238:239]
	global_store_dwordx4 v[92:93], v[68:71], off offset:512
	s_nop 0
	v_lshl_add_u64 v[78:79], v[136:137], 0, s[28:29]
	s_mov_b32 s28, 0xfff80000
	v_cndmask_b32_e32 v77, v141, v149, vcc
	v_cndmask_b32_e32 v76, v150, v151, vcc
	s_mov_b32 s29, -1
	v_lshl_add_u64 v[76:77], v[76:77], 0, v[142:143]
	v_lshl_add_u64 v[80:81], v[138:139], 0, s[28:29]
	v_cndmask_b32_e64 v81, v81, v79, s[8:9]
	v_cndmask_b32_e64 v80, v80, v78, s[8:9]
	s_mov_b64 s[28:29], 0x90000
	s_waitcnt vmcnt(3)
	v_pk_fma_f32 v[66:67], v[66:67], v[228:229], v[244:245]
	v_pk_fma_f32 v[64:65], v[64:65], v[226:227], v[242:243]
	global_store_dwordx4 v[92:93], v[64:67], off offset:576
	global_load_dwordx4 v[230:233], v[80:81], off
	global_load_dwordx4 v[234:237], v[80:81], off offset:64
	global_load_dwordx4 v[238:241], v[80:81], off offset:512
	global_load_dwordx4 v[242:245], v[80:81], off offset:576
	s_nop 0
	v_add_co_u32_e32 v72, vcc, s87, v136
	s_waitcnt vmcnt(3)
	v_pk_fma_f32 v[62:63], v[62:63], v[216:217], v[232:233]
	v_addc_co_u32_e32 v73, vcc, 0, v137, vcc
	v_pk_fma_f32 v[60:61], v[60:61], v[214:215], v[230:231]
	global_store_dwordx4 v[72:73], v[60:63], off
	s_nop 0
	v_cmp_gt_i32_e32 vcc, s40, v140
	s_waitcnt vmcnt(3)
; #define PG8_WAIT_V(n) asm volatile("s_waitcnt vmcnt(" #n ")" ::: "memory")
; #define PG8_BAR __builtin_amdgcn_s_barrier()
; template <class Epi, class Sched>
; __device__ __forceinline__ void gemm_phase(LAS unsigned char* lds, const Gemm g, const Sched& S, const Epi& E) {
;     ...
;     E(acc, cur, wr, wc, fr, fq);
;     if (!has_next) break;
; #pragma unroll
;     for (int a = 0; a < 2; ++a)
; #pragma unroll
;       for (int b = 0; b < 2; ++b)
; #pragma unroll
;         for (int m = 0; m < 4; ++m)
; #pragma unroll
;           for (int n = 0; n < 2; ++n) acc[a][b][m][n] = (f32x4){0.f, 0.f, 0.f, 0.f};
;     cur = nxt; cA = nA; cB = nB; ++ui;
;   }
;   PG8_WAIT_V(0);
;   if (wr == 0) PG8_BAR;
;   PG8_BAR;
	v_pk_fma_f32 v[58:59], v[58:59], v[220:221], v[236:237]
	v_pk_fma_f32 v[56:57], v[56:57], v[218:219], v[234:235]
	global_store_dwordx4 v[78:79], v[56:59], off offset:64
	s_nop 0
	s_waitcnt vmcnt(3)
	v_pk_fma_f32 v[54:55], v[54:55], v[224:225], v[240:241]
	v_pk_fma_f32 v[52:53], v[52:53], v[222:223], v[238:239]
	global_store_dwordx4 v[78:79], v[52:55], off offset:512
	s_nop 0
	v_lshl_add_u64 v[62:63], v[136:137], 0, s[28:29]
	s_mov_b32 s28, 0xfff90000
	v_cndmask_b32_e32 v61, v141, v149, vcc
	v_cndmask_b32_e32 v60, v150, v151, vcc
	s_mov_b32 s29, -1
	v_lshl_add_u64 v[60:61], v[60:61], 0, v[142:143]
	v_lshl_add_u64 v[64:65], v[138:139], 0, s[28:29]
	v_cndmask_b32_e64 v65, v65, v63, s[8:9]
	v_cndmask_b32_e64 v64, v64, v62, s[8:9]
	s_mov_b64 s[28:29], 0xa0000
	s_waitcnt vmcnt(3)
	v_pk_fma_f32 v[46:47], v[46:47], v[228:229], v[244:245]
	v_pk_fma_f32 v[44:45], v[44:45], v[226:227], v[242:243]
	global_store_dwordx4 v[78:79], v[44:47], off offset:576
	global_load_dwordx4 v[230:233], v[64:65], off
	global_load_dwordx4 v[234:237], v[64:65], off offset:64
	global_load_dwordx4 v[238:241], v[64:65], off offset:512
	global_load_dwordx4 v[242:245], v[64:65], off offset:576
	s_nop 0
	v_add_co_u32_e32 v56, vcc, s19, v136
	s_mov_b32 s19, 0xa0000
	s_nop 0
	v_addc_co_u32_e32 v57, vcc, 0, v137, vcc
	v_cmp_gt_i32_e32 vcc, s91, v140
	s_waitcnt vmcnt(3)
	v_pk_fma_f32 v[46:47], v[50:51], v[216:217], v[232:233]
	v_pk_fma_f32 v[44:45], v[48:49], v[214:215], v[230:231]
	global_store_dwordx4 v[56:57], v[44:47], off
	s_nop 0
	s_waitcnt vmcnt(3)
	v_pk_fma_f32 v[42:43], v[42:43], v[220:221], v[236:237]
	v_pk_fma_f32 v[40:41], v[40:41], v[218:219], v[234:235]
	global_store_dwordx4 v[62:63], v[40:43], off offset:64
	s_nop 0
	s_waitcnt vmcnt(3)
	v_pk_fma_f32 v[38:39], v[38:39], v[224:225], v[240:241]
	v_pk_fma_f32 v[36:37], v[36:37], v[222:223], v[238:239]
	global_store_dwordx4 v[62:63], v[36:39], off offset:512
	s_nop 0
	v_lshl_add_u64 v[46:47], v[136:137], 0, s[28:29]
	s_mov_b32 s28, 0xfffa0000
	v_cndmask_b32_e32 v45, v141, v149, vcc
	v_cndmask_b32_e32 v44, v150, v151, vcc
	s_mov_b32 s29, -1
	v_lshl_add_u64 v[44:45], v[44:45], 0, v[142:143]
	v_lshl_add_u64 v[48:49], v[138:139], 0, s[28:29]
	v_cndmask_b32_e64 v49, v49, v47, s[8:9]
	v_cndmask_b32_e64 v48, v48, v46, s[8:9]
	s_mov_b64 s[28:29], 0xb0000
	s_waitcnt vmcnt(3)
	v_pk_fma_f32 v[30:31], v[30:31], v[228:229], v[244:245]
	v_pk_fma_f32 v[28:29], v[28:29], v[226:227], v[242:243]
	global_store_dwordx4 v[62:63], v[28:31], off offset:576
	global_load_dwordx4 v[230:233], v[48:49], off
	global_load_dwordx4 v[234:237], v[48:49], off offset:64
	global_load_dwordx4 v[238:241], v[48:49], off offset:512
	global_load_dwordx4 v[242:245], v[48:49], off offset:576
	s_nop 0
	v_add_co_u32_e32 v40, vcc, s19, v136
	s_mov_b32 s19, 0xb0000
	s_nop 0
	v_addc_co_u32_e32 v41, vcc, 0, v137, vcc
	v_cmp_gt_i32_e32 vcc, s41, v140
	s_waitcnt vmcnt(3)
	v_pk_fma_f32 v[30:31], v[34:35], v[216:217], v[232:233]
	v_pk_fma_f32 v[28:29], v[32:33], v[214:215], v[230:231]
	global_store_dwordx4 v[40:41], v[28:31], off
	s_nop 0
	s_waitcnt vmcnt(3)
	v_pk_fma_f32 v[26:27], v[26:27], v[220:221], v[236:237]
	v_pk_fma_f32 v[24:25], v[24:25], v[218:219], v[234:235]
	global_store_dwordx4 v[46:47], v[24:27], off offset:64
	s_nop 0
	s_waitcnt vmcnt(3)
	v_pk_fma_f32 v[22:23], v[22:23], v[224:225], v[240:241]
	v_pk_fma_f32 v[20:21], v[20:21], v[222:223], v[238:239]
	global_store_dwordx4 v[46:47], v[20:23], off offset:512
	s_nop 0
	v_lshl_add_u64 v[30:31], v[136:137], 0, s[28:29]
	s_mov_b32 s28, 0xfffb0000
	v_cndmask_b32_e32 v29, v141, v149, vcc
	v_cndmask_b32_e32 v28, v150, v151, vcc
	s_mov_b32 s29, -1
	v_lshl_add_u64 v[28:29], v[28:29], 0, v[142:143]
	v_lshl_add_u64 v[32:33], v[138:139], 0, s[28:29]
	v_cndmask_b32_e64 v33, v33, v31, s[8:9]
	v_cndmask_b32_e64 v32, v32, v30, s[8:9]
	s_mov_b64 s[28:29], s[22:23]
	s_waitcnt vmcnt(3)
	v_pk_fma_f32 v[14:15], v[14:15], v[228:229], v[244:245]
	v_pk_fma_f32 v[12:13], v[12:13], v[226:227], v[242:243]
	global_store_dwordx4 v[46:47], v[12:15], off offset:576
	global_load_dwordx4 v[230:233], v[32:33], off
	global_load_dwordx4 v[234:237], v[32:33], off offset:64
	global_load_dwordx4 v[238:241], v[32:33], off offset:512
	global_load_dwordx4 v[242:245], v[32:33], off offset:576
	s_nop 0
	v_add_co_u32_e32 v24, vcc, s19, v136
	s_waitcnt vmcnt(3)
	v_pk_fma_f32 v[14:15], v[18:19], v[216:217], v[232:233]
	v_addc_co_u32_e32 v25, vcc, 0, v137, vcc
	v_pk_fma_f32 v[12:13], v[16:17], v[214:215], v[230:231]
	global_store_dwordx4 v[24:25], v[12:15], off
	s_nop 0
	s_and_b64 vcc, exec, s[10:11]
	s_waitcnt vmcnt(3)
	v_pk_fma_f32 v[10:11], v[10:11], v[220:221], v[236:237]
	v_pk_fma_f32 v[8:9], v[8:9], v[218:219], v[234:235]
	global_store_dwordx4 v[30:31], v[8:11], off offset:64
	s_nop 0
	s_waitcnt vmcnt(3)
	v_pk_fma_f32 v[6:7], v[6:7], v[224:225], v[240:241]
	v_pk_fma_f32 v[4:5], v[4:5], v[222:223], v[238:239]
	global_store_dwordx4 v[30:31], v[4:7], off offset:512
	s_nop 0
	s_waitcnt vmcnt(3)
	v_pk_fma_f32 v[2:3], v[2:3], v[228:229], v[244:245]
	v_pk_fma_f32 v[0:1], v[0:1], v[226:227], v[242:243]
	global_store_dwordx4 v[30:31], v[0:3], off offset:576
	s_cbranch_vccz .LBB0_2626
	s_waitcnt vmcnt(0)
	v_readlane_b32 s82, v255, 17
	v_readlane_b32 s68, v255, 20
	s_cmpk_gt_u32 s24, 0xff
	v_readlane_b32 s83, v255, 18
	s_mov_b32 s74, 0x8000
	s_mov_b32 s75, 0x10000
	s_movk_i32 s79, 0x40ff
	s_movk_i32 s78, 0x2000
	v_readlane_b32 s69, v255, 21
	v_readlane_b32 s59, v255, 19
	s_cbranch_scc1 .LBB0_2637
	s_barrier

.LBB0_2880:
	s_nop 1
	v_or_b32_e32 v114, 16, v138
	v_ashrrev_i32_e32 v115, 31, v114
	v_lshlrev_b64 v[112:113], 12, v[114:115]
	v_mov_b32_e32 v115, s51
	v_mov_b32_e32 v116, s59
	v_cmp_gt_i32_e32 vcc, s73, v114
	v_lshl_add_u64 v[112:113], s[14:15], 0, v[112:113]
	v_lshl_add_u64 v[112:113], v[112:113], 0, v[140:141]
	v_cndmask_b32_e32 v117, v115, v116, vcc
	v_mov_b32_e32 v115, s49
	v_mov_b32_e32 v116, s58
	v_cndmask_b32_e32 v116, v115, v116, vcc
	v_lshl_add_u64 v[116:117], v[116:117], 0, v[140:141]
	global_load_dwordx4 v[230:233], v[112:113], off
	global_load_dwordx4 v[234:237], v[112:113], off offset:64
	global_load_dwordx4 v[238:241], v[112:113], off offset:512
	global_load_dwordx4 v[242:245], v[112:113], off offset:576
	v_add_u32_e32 v126, 0xffffff10, v138
	v_mov_b32_e32 v127, v144
	s_and_b64 vcc, exec, s[8:9]
	v_cmp_lt_i32_e64 s[10:11], s81, v114
	v_lshlrev_b64 v[114:115], 12, v[126:127]
	s_waitcnt vmcnt(3)
	v_pk_fma_f32 v[110:111], v[110:111], v[216:217], v[232:233]
	v_pk_fma_f32 v[108:109], v[108:109], v[214:215], v[230:231]
	s_cbranch_vccnz .LBB0_3023
	s_and_saveexec_b64 s[24:25], s[10:11]
	s_cbranch_execz .LBB0_2883
	v_lshl_add_u64 v[118:119], s[16:17], 0, v[114:115]
	v_lshl_add_u64 v[118:119], v[136:137], 2, v[118:119]
	global_store_dwordx4 v[118:119], v[108:111], off

.LBB0_2900:
	s_nop 1
	v_or_b32_e32 v98, 32, v138
	v_ashrrev_i32_e32 v99, 31, v98
	v_lshlrev_b64 v[96:97], 12, v[98:99]
	v_mov_b32_e32 v99, s51
	v_mov_b32_e32 v100, s59
	v_cmp_gt_i32_e32 vcc, s73, v98
	v_lshl_add_u64 v[96:97], s[14:15], 0, v[96:97]
	v_lshl_add_u64 v[96:97], v[96:97], 0, v[140:141]
	v_cndmask_b32_e32 v101, v99, v100, vcc
	v_mov_b32_e32 v99, s49
	v_mov_b32_e32 v100, s58
	v_cndmask_b32_e32 v100, v99, v100, vcc
	v_lshl_add_u64 v[100:101], v[100:101], 0, v[140:141]
	global_load_dwordx4 v[230:233], v[96:97], off
	global_load_dwordx4 v[234:237], v[96:97], off offset:64
	global_load_dwordx4 v[238:241], v[96:97], off offset:512
	global_load_dwordx4 v[242:245], v[96:97], off offset:576
	v_add_u32_e32 v110, 0xffffff20, v138
	v_mov_b32_e32 v111, v144
	s_and_b64 vcc, exec, s[8:9]
	v_cmp_lt_i32_e64 s[10:11], s81, v98
	v_lshlrev_b64 v[98:99], 12, v[110:111]
	s_waitcnt vmcnt(3)
	v_pk_fma_f32 v[94:95], v[94:95], v[216:217], v[232:233]
	v_pk_fma_f32 v[92:93], v[92:93], v[214:215], v[230:231]
	s_cbranch_vccnz .LBB0_3027
	s_and_saveexec_b64 s[24:25], s[10:11]
	s_cbranch_execz .LBB0_2903
	v_lshl_add_u64 v[102:103], s[16:17], 0, v[98:99]
	v_lshl_add_u64 v[102:103], v[136:137], 2, v[102:103]
	global_store_dwordx4 v[102:103], v[92:95], off

.LBB0_2920:
	s_nop 1
	v_or_b32_e32 v82, 48, v138
	v_ashrrev_i32_e32 v83, 31, v82
	v_lshlrev_b64 v[80:81], 12, v[82:83]
	v_mov_b32_e32 v83, s51
	v_mov_b32_e32 v84, s59
	v_cmp_gt_i32_e32 vcc, s73, v82
	v_lshl_add_u64 v[80:81], s[14:15], 0, v[80:81]
	v_lshl_add_u64 v[80:81], v[80:81], 0, v[140:141]
	v_cndmask_b32_e32 v85, v83, v84, vcc
	v_mov_b32_e32 v83, s49
	v_mov_b32_e32 v84, s58
	v_cndmask_b32_e32 v84, v83, v84, vcc
	v_lshl_add_u64 v[84:85], v[84:85], 0, v[140:141]
	global_load_dwordx4 v[230:233], v[80:81], off
	global_load_dwordx4 v[234:237], v[80:81], off offset:64
	global_load_dwordx4 v[238:241], v[80:81], off offset:512
	global_load_dwordx4 v[242:245], v[80:81], off offset:576
	v_add_u32_e32 v94, 0xffffff30, v138
	v_mov_b32_e32 v95, v144
	s_and_b64 vcc, exec, s[8:9]
	v_cmp_lt_i32_e64 s[10:11], s81, v82
	v_lshlrev_b64 v[82:83], 12, v[94:95]
	s_waitcnt vmcnt(3)
	v_pk_fma_f32 v[78:79], v[78:79], v[216:217], v[232:233]
	v_pk_fma_f32 v[76:77], v[76:77], v[214:215], v[230:231]
	s_cbranch_vccnz .LBB0_3031
	s_and_saveexec_b64 s[24:25], s[10:11]
	s_cbranch_execz .LBB0_2923
	v_lshl_add_u64 v[86:87], s[16:17], 0, v[82:83]
	v_lshl_add_u64 v[86:87], v[136:137], 2, v[86:87]
	global_store_dwordx4 v[86:87], v[76:79], off

.LBB0_2940:
	s_movk_i32 s10, 0x80
	s_nop 0
	v_lshlrev_b64 v[64:65], 12, v[138:139]
	v_mov_b32_e32 v66, s51
	v_mov_b32_e32 v67, s59
	v_cmp_gt_i32_e32 vcc, s10, v138
	v_mov_b32_e32 v68, s58
	v_lshl_add_u64 v[64:65], s[14:15], 0, v[64:65]
	v_cndmask_b32_e32 v67, v66, v67, vcc
	v_mov_b32_e32 v66, s49
	v_cndmask_b32_e32 v66, v66, v68, vcc
	v_lshl_add_u64 v[68:69], v[64:65], 0, v[140:141]
	v_add_co_u32_e32 v64, vcc, 0x80000, v68
	v_lshl_add_u64 v[66:67], v[66:67], 0, v[140:141]
	s_nop 0
	v_addc_co_u32_e32 v65, vcc, 0, v69, vcc
	global_load_dwordx4 v[230:233], v[64:65], off
	global_load_dwordx4 v[234:237], v[64:65], off offset:64
	global_load_dwordx4 v[238:241], v[64:65], off offset:512
	global_load_dwordx4 v[242:245], v[64:65], off offset:576
	v_add_u32_e32 v64, 0xffffff80, v138
	s_movk_i32 s10, 0x7f
	v_mov_b32_e32 v65, v144
	v_cmp_lt_i32_e64 s[10:11], s10, v138
	v_lshlrev_b64 v[64:65], 12, v[64:65]
	s_and_b64 vcc, exec, s[8:9]
	s_waitcnt vmcnt(3)
	v_pk_fma_f32 v[62:63], v[62:63], v[216:217], v[232:233]
	v_pk_fma_f32 v[60:61], v[60:61], v[214:215], v[230:231]
	s_cbranch_vccnz .LBB0_3035
	s_and_saveexec_b64 s[24:25], s[10:11]
	s_cbranch_execz .LBB0_2943
	v_lshl_add_u64 v[70:71], s[16:17], 0, v[64:65]
	v_lshl_add_u64 v[70:71], v[136:137], 2, v[70:71]
	global_store_dwordx4 v[70:71], v[60:63], off

.LBB0_2960:
	s_nop 1
	v_lshlrev_b64 v[48:49], 12, v[138:139]
	v_mov_b32_e32 v50, s51
	v_mov_b32_e32 v51, s59
	v_cmp_gt_i32_e32 vcc, s40, v138
	v_mov_b32_e32 v52, s58
	v_lshl_add_u64 v[48:49], s[14:15], 0, v[48:49]
	v_cndmask_b32_e32 v51, v50, v51, vcc
	v_mov_b32_e32 v50, s49
	v_cndmask_b32_e32 v50, v50, v52, vcc
	v_lshl_add_u64 v[52:53], v[48:49], 0, v[140:141]
	v_add_co_u32_e32 v48, vcc, 0x90000, v52
	v_lshl_add_u64 v[50:51], v[50:51], 0, v[140:141]
	s_nop 0
	v_addc_co_u32_e32 v49, vcc, 0, v53, vcc
	global_load_dwordx4 v[230:233], v[48:49], off
	global_load_dwordx4 v[234:237], v[48:49], off offset:64
	global_load_dwordx4 v[238:241], v[48:49], off offset:512
	global_load_dwordx4 v[242:245], v[48:49], off offset:576
	v_add_u32_e32 v48, 0xffffff90, v138
	s_movk_i32 s10, 0x6f
	v_mov_b32_e32 v49, v144
	v_cmp_lt_i32_e64 s[10:11], s10, v138
	v_lshlrev_b64 v[48:49], 12, v[48:49]
	s_and_b64 vcc, exec, s[8:9]
	s_waitcnt vmcnt(3)
	v_pk_fma_f32 v[46:47], v[46:47], v[216:217], v[232:233]
	v_pk_fma_f32 v[44:45], v[44:45], v[214:215], v[230:231]
	s_cbranch_vccnz .LBB0_3039
	s_and_saveexec_b64 s[24:25], s[10:11]
	s_cbranch_execz .LBB0_2963
	v_lshl_add_u64 v[54:55], s[16:17], 0, v[48:49]
	v_lshl_add_u64 v[54:55], v[136:137], 2, v[54:55]
	global_store_dwordx4 v[54:55], v[44:47], off

.LBB0_2980:
	s_nop 1
	v_lshlrev_b64 v[32:33], 12, v[138:139]
	v_mov_b32_e32 v34, s51
	v_mov_b32_e32 v35, s59
	v_cmp_gt_i32_e32 vcc, s91, v138
	v_mov_b32_e32 v36, s58
	v_lshl_add_u64 v[32:33], s[14:15], 0, v[32:33]
	v_cndmask_b32_e32 v35, v34, v35, vcc
	v_mov_b32_e32 v34, s49
	v_cndmask_b32_e32 v34, v34, v36, vcc
	v_lshl_add_u64 v[36:37], v[32:33], 0, v[140:141]
	v_add_co_u32_e32 v32, vcc, 0xa0000, v36
	v_lshl_add_u64 v[34:35], v[34:35], 0, v[140:141]
	s_nop 0
	v_addc_co_u32_e32 v33, vcc, 0, v37, vcc
	global_load_dwordx4 v[230:233], v[32:33], off
	global_load_dwordx4 v[234:237], v[32:33], off offset:64
	global_load_dwordx4 v[238:241], v[32:33], off offset:512
	global_load_dwordx4 v[242:245], v[32:33], off offset:576
	v_add_u32_e32 v32, 0xffffffa0, v138
	s_movk_i32 s10, 0x5f
	v_mov_b32_e32 v33, v144
	v_cmp_lt_i32_e64 s[10:11], s10, v138
	v_lshlrev_b64 v[32:33], 12, v[32:33]
	s_and_b64 vcc, exec, s[8:9]
	s_waitcnt vmcnt(3)
	v_pk_fma_f32 v[30:31], v[30:31], v[216:217], v[232:233]
	v_pk_fma_f32 v[28:29], v[28:29], v[214:215], v[230:231]
	s_cbranch_vccnz .LBB0_3043
	s_and_saveexec_b64 s[24:25], s[10:11]
	s_cbranch_execz .LBB0_2983
	v_lshl_add_u64 v[38:39], s[16:17], 0, v[32:33]
	v_lshl_add_u64 v[38:39], v[136:137], 2, v[38:39]
	global_store_dwordx4 v[38:39], v[28:31], off

.LBB0_3000:
	s_nop 1
	v_lshlrev_b64 v[16:17], 12, v[138:139]
	v_mov_b32_e32 v18, s51
	v_mov_b32_e32 v19, s59
	v_cmp_gt_i32_e32 vcc, s41, v138
	v_mov_b32_e32 v20, s58
	v_lshl_add_u64 v[16:17], s[14:15], 0, v[16:17]
	v_cndmask_b32_e32 v19, v18, v19, vcc
	v_mov_b32_e32 v18, s49
	v_cndmask_b32_e32 v18, v18, v20, vcc
	v_lshl_add_u64 v[20:21], v[16:17], 0, v[140:141]
	v_add_co_u32_e32 v16, vcc, 0xb0000, v20
	v_lshl_add_u64 v[18:19], v[18:19], 0, v[140:141]
	s_nop 0
	v_addc_co_u32_e32 v17, vcc, 0, v21, vcc
	global_load_dwordx4 v[230:233], v[16:17], off
	global_load_dwordx4 v[234:237], v[16:17], off offset:64
	global_load_dwordx4 v[238:241], v[16:17], off offset:512
	global_load_dwordx4 v[242:245], v[16:17], off offset:576
	v_add_u32_e32 v16, 0xffffffb0, v138
	s_movk_i32 s10, 0x4f
	v_mov_b32_e32 v17, v144
	v_cmp_lt_i32_e64 s[10:11], s10, v138
	v_lshlrev_b64 v[16:17], 12, v[16:17]
	s_and_b64 vcc, exec, s[8:9]
	s_waitcnt vmcnt(3)
	v_pk_fma_f32 v[14:15], v[14:15], v[216:217], v[232:233]
	v_pk_fma_f32 v[12:13], v[12:13], v[214:215], v[230:231]
	s_cbranch_vccnz .LBB0_3047
	s_and_saveexec_b64 s[24:25], s[10:11]
	s_cbranch_execz .LBB0_3003
	v_lshl_add_u64 v[22:23], s[16:17], 0, v[16:17]
	v_lshl_add_u64 v[22:23], v[136:137], 2, v[22:23]
	global_store_dwordx4 v[22:23], v[12:15], off
